# sample-attention loop slimmed: dead zero-inits and bool materialisation removed, LDS write addresses via immediate offsets, tile loads through SGPR base plus one per-lane offset
# speedup vs baseline: 1.0080x; 1.0033x over previous
; #define LAS __attribute__((address_space(3)))
; #define MFMA16(a, b, c) __builtin_amdgcn_mfma_f32_16x16x32_bf16((a), (b), (c), 0, 0, 0)
; DI void attn_sample_phase(const Args& a, LAS unsigned char* lds, int vcu, int G, int tid, int lane, int wave) {
;     ...
;             { const LAS unsigned char* c8b = C8 + (j & 1) * 8704; const LAS float* spe = SSPE + (j & 1) * 32;
; #pragma unroll
;                 for (int kb = 0; kb < 2; ++kb) { f32x4 acc[4] = {};
; #pragma unroll
;                     for (int ks = 0; ks < 2; ++ks) { const LAS unsigned char* ap = c8b + (kb * 16 + r16) * 272 + 128 * ks + 32 * q4;
;                         const u32x4 x0 = *(const LAS u32x4*)ap, x1 = *(const LAS u32x4*)(ap + 16);
;                         const v8i_t af = {(int)x0.x, (int)x0.y, (int)x0.z, (int)x0.w, (int)x1.x, (int)x1.y, (int)x1.z, (int)x1.w};
; #pragma unroll
;                         for (int nb = 0; nb < 4; ++nb) acc[nb] = __builtin_amdgcn_mfma_scale_f32_16x16x128_f8f6f4(af, wf8[nb][ks], acc[nb], 0, 0, 0, 0x7F7F7F7F, 0, 0x7F7F7F7F); }
;                     f32x4 sq = (acc[0] * acc[0] + acc[1] * acc[1] + acc[2] * acc[2] + acc[3] * acc[3]) * (1.f / 256.f);
;                     sq.x = row16_sum(sq.x); sq.y = row16_sum(sq.y); sq.z = row16_sum(sq.z); sq.w = row16_sum(sq.w);
;                     if (r16 == 0) { const f32x4 pe = *(const LAS f32x4*)(spe + kb * 16 + 4 * q4); f32x4 r;
;                         r.x = __builtin_amdgcn_rsqf((sq.x + pe.x) * (1.f / 96.f) + EPS); r.y = __builtin_amdgcn_rsqf((sq.y + pe.y) * (1.f / 96.f) + EPS);
;                         r.z = __builtin_amdgcn_rsqf((sq.z + pe.z) * (1.f / 96.f) + EPS); r.w = __builtin_amdgcn_rsqf((sq.w + pe.w) * (1.f / 96.f) + EPS);
;                         *(LAS f32x4*)(RI + wave * 32 + kb * 16 + 4 * q4) = r; } } }
;             f32x4 sa = {0.f, 0.f, 0.f, 0.f};
;             if (wave < 4) { const int kb = wave >> 1, nb2 = wave & 1; const LAS bf16* cb = Cs + c3 * (32 * CSW);
; #pragma unroll
;                 for (int s9 = 0; s9 < 9; ++s9) { const bf16x8 af = *(const LAS bf16x8*)(cb + (kb * 16 + r16) * CSW + 32 * s9 + 8 * q4);
;                     sa = MFMA16(af, qfr[s9], sa); } (void)nb2; }
.LBB0_904:
	s_add_i32 s26, s25, -2
	s_and_b32 s8, s26, 1
	s_mul_i32 s9, s8, 0x2200
	v_add_u32_e32 v2, s9, v202
	s_lshl_b32 s8, s8, 7
	s_add_i32 s8, s8, 0x17a00
	v_lshl_add_u32 v254, v140, 2, s8
	ds_read_b128 v[212:215], v2 offset:56832
	ds_read_b128 v[216:219], v2 offset:56848
	ds_read_b128 v[236:239], v2 offset:56960
	ds_read_b128 v[240:243], v2 offset:56976
	ds_read_b128 v[246:249], v2 offset:61184
	ds_read_b128 v[250:253], v2 offset:61200
	ds_read_b32 v232, v254
	ds_read_b32 v233, v254 offset:64
	s_waitcnt lgkmcnt(6)
	v_mfma_scale_f32_16x16x128_f8f6f4 v[220:223], v[36:43], v[212:219], 0, v208, v208 op_sel_hi:[0,0,0]
	v_mfma_scale_f32_16x16x128_f8f6f4 v[136:139], v[20:27], v[212:219], 0, v208, v208 op_sel_hi:[0,0,0]
	v_mfma_scale_f32_16x16x128_f8f6f4 v[224:227], v[52:59], v[212:219], 0, v208, v208 op_sel_hi:[0,0,0]
	v_mfma_scale_f32_16x16x128_f8f6f4 v[228:231], v[68:75], v[212:219], 0, v208, v208 op_sel_hi:[0,0,0]
	s_waitcnt lgkmcnt(4)
	v_mfma_scale_f32_16x16x128_f8f6f4 v[220:223], v[44:51], v[236:243], v[220:223], v208, v208 op_sel_hi:[0,0,0]
	ds_read_b128 v[212:215], v2 offset:61312
	ds_read_b128 v[216:219], v2 offset:61328
	v_mfma_scale_f32_16x16x128_f8f6f4 v[136:139], v[28:35], v[236:243], v[136:139], v208, v208 op_sel_hi:[0,0,0]
	v_mfma_scale_f32_16x16x128_f8f6f4 v[224:227], v[60:67], v[236:243], v[224:227], v208, v208 op_sel_hi:[0,0,0]
	v_mfma_scale_f32_16x16x128_f8f6f4 v[228:231], v[76:83], v[236:243], v[228:231], v208, v208 op_sel_hi:[0,0,0]
	v_lshlrev_b32_e32 v255, 7, v158
	v_lshl_add_u32 v255, v140, 2, v255
	v_add_u32_e32 v255, 0x17600, v255
	s_mov_b64 s[100:101], 0xffff
	s_nop 4
	v_mul_f32_e32 v234, v220, v220
	v_fmac_f32_e32 v234, v221, v221
	v_fmac_f32_e32 v234, v222, v222
	v_fmac_f32_e32 v234, v223, v223
	s_waitcnt lgkmcnt(4)
	v_mfma_scale_f32_16x16x128_f8f6f4 v[220:223], v[36:43], v[246:253], 0, v208, v208 op_sel_hi:[0,0,0]
	v_fmac_f32_e32 v234, v136, v136
	v_fmac_f32_e32 v234, v137, v137
	v_fmac_f32_e32 v234, v138, v138
	v_fmac_f32_e32 v234, v139, v139
	v_mfma_scale_f32_16x16x128_f8f6f4 v[136:139], v[68:75], v[246:253], 0, v208, v208 op_sel_hi:[0,0,0]
	v_fmac_f32_e32 v234, v224, v224
	v_fmac_f32_e32 v234, v225, v225
	v_fmac_f32_e32 v234, v226, v226
	v_fmac_f32_e32 v234, v227, v227
	v_mfma_scale_f32_16x16x128_f8f6f4 v[224:227], v[20:27], v[246:253], 0, v208, v208 op_sel_hi:[0,0,0]
	v_fmac_f32_e32 v234, v228, v228
	v_fmac_f32_e32 v234, v229, v229
	v_fmac_f32_e32 v234, v230, v230
	v_fmac_f32_e32 v234, v231, v231
	v_mfma_scale_f32_16x16x128_f8f6f4 v[228:231], v[52:59], v[246:253], 0, v208, v208 op_sel_hi:[0,0,0]
	s_waitcnt lgkmcnt(0)
	v_mov_b32_e32 v235, v234
	v_mfma_scale_f32_16x16x128_f8f6f4 v[220:223], v[44:51], v[212:219], v[220:223], v208, v208 op_sel_hi:[0,0,0]
	s_nop 0
	v_permlane32_swap_b32_e32 v235, v234
	v_add_f32_e32 v234, v234, v235
	v_mfma_scale_f32_16x16x128_f8f6f4 v[136:139], v[76:83], v[212:219], v[136:139], v208, v208 op_sel_hi:[0,0,0]
	v_mov_b32_e32 v235, v234
	s_nop 1
	v_permlane16_swap_b32_e32 v235, v234
	v_add_f32_e32 v234, v234, v235
	v_mfma_scale_f32_16x16x128_f8f6f4 v[224:227], v[28:35], v[212:219], v[224:227], v208, v208 op_sel_hi:[0,0,0]
	v_fmamk_f32 v234, v234, 0x3b800000, v232
	v_fmamk_f32 v234, v234, 0x3c2aaaab, v209
	v_rsq_f32_e32 v234, v234
	v_mfma_scale_f32_16x16x128_f8f6f4 v[228:231], v[60:67], v[212:219], v[228:231], v208, v208 op_sel_hi:[0,0,0]
	s_and_saveexec_b64 s[18:19], s[100:101]
	ds_write_b32 v255, v234
	s_or_b64 exec, exec, s[18:19]
	v_mul_f32_e32 v234, v220, v220
	v_fmac_f32_e32 v234, v221, v221
	v_fmac_f32_e32 v234, v222, v222
	v_fmac_f32_e32 v234, v223, v223
	v_fmac_f32_e32 v234, v136, v136
	v_fmac_f32_e32 v234, v137, v137
	v_fmac_f32_e32 v234, v138, v138
	v_fmac_f32_e32 v234, v139, v139
	v_fmac_f32_e32 v234, v224, v224
	v_fmac_f32_e32 v234, v225, v225
	v_fmac_f32_e32 v234, v226, v226
	v_fmac_f32_e32 v234, v227, v227
	v_fmac_f32_e32 v234, v228, v228
	v_fmac_f32_e32 v234, v229, v229
	v_fmac_f32_e32 v234, v230, v230
	v_fmac_f32_e32 v234, v231, v231
	v_mov_b32_e32 v235, v234
	s_nop 1
	v_permlane32_swap_b32_e32 v235, v234
	v_add_f32_e32 v234, v234, v235
	v_mov_b32_e32 v235, v234
	s_nop 1
	v_permlane16_swap_b32_e32 v235, v234
	v_add_f32_e32 v234, v234, v235
	v_fmamk_f32 v234, v234, 0x3b800000, v233
	v_fmamk_f32 v234, v234, 0x3c2aaaab, v209
	v_rsq_f32_e32 v234, v234
	s_and_saveexec_b64 s[18:19], s[100:101]
	ds_write_b32 v255, v234 offset:64
	s_or_b64 exec, exec, s[18:19]
.LBB0_908:
	s_andn2_b64 s[8:9], exec, s[10:11]
	s_andn2_b64 vcc, exec, s[10:11]
	s_cbranch_vccnz .LBB0_910
	s_mul_i32 s18, s98, 0x4a00
	v_add_u32_e32 v2, s18, v197
	ds_read_b128 v[136:139], v2
	ds_read_b128 v[212:215], v2 offset:64
	ds_read_b128 v[216:219], v2 offset:128
	s_waitcnt lgkmcnt(2)
	v_mfma_f32_16x16x32_bf16 v[136:139], v[136:139], v[84:87], 0
	s_waitcnt lgkmcnt(1)
	v_mfma_f32_16x16x32_bf16 v[136:139], v[212:215], v[88:91], v[136:139]
	ds_read_b128 v[212:215], v2 offset:192
	s_waitcnt lgkmcnt(1)
	v_mfma_f32_16x16x32_bf16 v[136:139], v[216:219], v[92:95], v[136:139]
	ds_read_b128 v[216:219], v2 offset:256
	s_waitcnt lgkmcnt(1)
	v_mfma_f32_16x16x32_bf16 v[136:139], v[212:215], v[96:99], v[136:139]
	ds_read_b128 v[212:215], v2 offset:320
	s_waitcnt lgkmcnt(1)
	v_mfma_f32_16x16x32_bf16 v[136:139], v[216:219], v[100:103], v[136:139]
	ds_read_b128 v[216:219], v2 offset:384
	s_waitcnt lgkmcnt(1)
	v_mfma_f32_16x16x32_bf16 v[136:139], v[212:215], v[104:107], v[136:139]
	ds_read_b128 v[212:215], v2 offset:448
	s_waitcnt lgkmcnt(1)
	v_mfma_f32_16x16x32_bf16 v[136:139], v[216:219], v[108:111], v[136:139]
	s_waitcnt lgkmcnt(0)
	v_mfma_f32_16x16x32_bf16 v[136:139], v[212:215], v[112:115], v[136:139]
	ds_read_b128 v[212:215], v2 offset:512
	s_waitcnt lgkmcnt(0)
	v_mfma_f32_16x16x32_bf16 v[136:139], v[212:215], v[116:119], v[136:139]

.Lsa_a4:
	s_add_i32 s18, s17, 1
	s_cmp_lg_u32 s17, 2
	s_cselect_b32 s17, s18, 0
	s_cmpk_eq_i32 s25, 0x81
	s_cbranch_scc1 .Lsa_a4end
	s_add_i32 s18, s25, -1
	s_and_b32 s28, s18, 1
	s_mul_i32 s27, s17, 0x4a00
	s_mul_i32 s18, s28, 0x2200
	v_add3_u32 v216, s18, v184, v180
	v_lshl_add_u32 v217, v181, 1, v182
	v_add_u32_e32 v217, s27, v217
	s_waitcnt vmcnt(3)
	v_cvt_pk_fp8_f32 v212, v120, v121
	v_cvt_pk_bf16_f32 v214, v120, v121
	v_cvt_pk_fp8_f32 v212, v122, v123 op_sel:[0,0,1]
	v_cvt_pk_bf16_f32 v215, v122, v123
	ds_write_b64 v217, v[214:215]
	ds_write_b32 v216, v212 offset:56832
	s_waitcnt vmcnt(2)
	v_cvt_pk_fp8_f32 v213, v124, v125
	v_cvt_pk_bf16_f32 v218, v124, v125
	v_cvt_pk_fp8_f32 v213, v126, v127 op_sel:[0,0,1]
	v_cvt_pk_bf16_f32 v219, v126, v127
	ds_write_b64 v217, v[218:219] offset:4736
	ds_write_b32 v216, v213 offset:59008
	s_waitcnt vmcnt(1)
	v_cvt_pk_fp8_f32 v212, v128, v129
	v_cvt_pk_bf16_f32 v214, v128, v129
	v_cvt_pk_fp8_f32 v212, v130, v131 op_sel:[0,0,1]
	v_cvt_pk_bf16_f32 v215, v130, v131
	ds_write_b64 v217, v[214:215] offset:9472
	ds_write_b32 v216, v212 offset:61184
	s_waitcnt vmcnt(0)
	v_cvt_pk_fp8_f32 v213, v132, v133
	v_cvt_pk_bf16_f32 v218, v132, v133
	v_cvt_pk_fp8_f32 v213, v134, v135 op_sel:[0,0,1]
	v_cvt_pk_bf16_f32 v219, v134, v135
	ds_write_b64 v217, v[218:219] offset:14208
	ds_write_b32 v216, v213 offset:63360
	s_and_saveexec_b64 s[18:19], s[2:3]
	s_cbranch_execz .LBB0_915
	v_pk_mul_f32 v[212:213], v[172:173], v[172:173]
	v_pk_mul_f32 v[214:215], v[174:175], v[174:175]
	v_add_f32_e32 v212, v212, v213
	v_add_f32_e32 v2, v214, v215
	v_add_f32_e32 v2, v212, v2
	v_mov_b32_e32 v212, 0
	s_nop 0
	v_add_f32_dpp v2, v2, v2 quad_perm:[1,0,3,2] row_mask:0xf bank_mask:0xf bound_ctrl:1
	s_nop 1
	v_add_f32_dpp v2, v2, v2 quad_perm:[2,3,0,1] row_mask:0xf bank_mask:0xf bound_ctrl:1
	s_nop 1
	v_mov_b32_dpp v212, v2 row_half_mirror row_mask:0xf bank_mask:0xf
	s_and_saveexec_b64 s[20:21], s[4:5]
	v_add_f32_e32 v2, v2, v212
	v_lshl_add_u32 v212, s28, 7, v191
	ds_write_b32 v212, v2
	s_or_b64 exec, exec, s[20:21]
	v_pk_mul_f32 v[214:215], v[146:147], v[174:175]
	v_pk_mul_f32 v[212:213], v[144:145], v[172:173]
	v_pk_mul_f32 v[216:217], v[214:215], v[178:179]
	s_nop 0
	v_pk_fma_f32 v[216:217], v[212:213], v[176:177], v[216:217] neg_lo:[0,0,1] neg_hi:[0,0,1]
	v_pk_mul_f32 v[212:213], v[212:213], v[178:179]
	v_cvt_pk_bf16_f32 v2, v216, v217
	v_pk_fma_f32 v[212:213], v[176:177], v[214:215], v[212:213]
	v_add3_u32 v214, s27, v192, v1
	v_cvt_pk_bf16_f32 v212, v212, v213
	ds_write2_b32 v214, v2, v212 offset0:128 offset1:136
	v_pk_mul_f32 v[212:213], v[150:151], v[178:179]
	v_pk_mul_f32 v[178:179], v[148:149], v[178:179]
	v_pk_fma_f32 v[212:213], v[148:149], v[176:177], v[212:213] neg_lo:[0,0,1] neg_hi:[0,0,1]
	v_pk_fma_f32 v[178:179], v[150:151], v[176:177], v[178:179]
	v_mov_b64_e32 v[176:177], v[212:213]
.LBB0_915:
	s_or_b64 exec, exec, s[18:19]
	s_cmpk_gt_u32 s26, 0x7d
	s_cbranch_scc1 .Lsa_a4end
	s_and_b32 s18, s25, -4
	s_add_i32 s18, s18, 0x17b80
	v_mov_b32_e32 v2, s18
	ds_read_b32 v2, v2
	s_and_b32 s20, s24, 0x60
	v_readfirstlane_b32 s100, v166
	v_readfirstlane_b32 s101, v167
	v_lshlrev_b32_e32 v212, 4, v0
	s_waitcnt lgkmcnt(0)
	v_readfirstlane_b32 s18, v2
	s_ashr_i32 s19, s18, 31
	s_lshl_b64 s[18:19], s[18:19], 7
	s_or_b32 s18, s18, s20
	s_lshl_b64 s[20:21], s[18:19], 10
	s_add_u32 s100, s100, s20
	s_addc_u32 s101, s101, s21
	global_load_dwordx4 v[120:123], v212, s[100:101] nt
	s_add_u32 s100, s100, 0x2000
	s_addc_u32 s101, s101, 0
	global_load_dwordx4 v[124:127], v212, s[100:101] nt
	s_add_u32 s100, s100, 0x2000
	s_addc_u32 s101, s101, 0
	global_load_dwordx4 v[128:131], v212, s[100:101] nt
	s_add_u32 s100, s100, 0x2000
	s_addc_u32 s101, s101, 0
	global_load_dwordx4 v[132:135], v212, s[100:101] nt
	s_and_saveexec_b64 s[20:21], s[2:3]
	s_cbranch_execz .LBB0_918
	v_mov_b32_e32 v173, s19
	v_or_b32_e32 v172, s18, v160
	v_lshlrev_b64 v[172:173], 7, v[172:173]
	v_lshl_add_u64 v[174:175], v[156:157], 0, v[172:173]
	global_load_dwordx2 v[172:173], v[174:175], off nt
	s_nop 0
	global_load_dwordx2 v[174:175], v[174:175], off offset:64 nt
